# PROJ GEMM also with swapped MFMA operands (C^T fragments, permuted weight-column mapping): no accumulator re-layout, epilogue packs 8 consecutive columns with cvt_pk and one ds_write_b128 per row bloc
# speedup vs baseline: 1.0312x; 1.0132x over previous
.LBB0_215:
	s_mul_hi_i32 s0, s8, 0x2aaaaaab
	s_lshr_b32 s1, s0, 31
	s_ashr_i32 s0, s0, 5
	s_add_i32 s0, s0, s1
	s_lshl_b32 s1, s0, 3
	s_sub_i32 s2, 17, s1
	s_min_u32 s2, s2, 8
	v_cvt_f32_ubyte0_e32 v0, s2
	v_rcp_iflag_f32_e32 v0, v0
	s_sub_i32 s5, 0, s2
	s_mulk_i32 s0, 0xff40
	s_add_i32 s3, s0, s8
	v_mul_f32_e32 v0, 0x4f7ffffe, v0
	v_cvt_u32_f32_e32 v0, v0
	s_abs_i32 s4, s3
	s_ashr_i32 s0, s3, 31
	v_mov_b32_e32 v181, v179
	v_readfirstlane_b32 s6, v0
	s_mul_i32 s5, s5, s6
	s_mul_hi_u32 s5, s6, s5
	s_add_i32 s6, s6, s5
	s_mul_hi_u32 s5, s4, s6
	s_mul_i32 s6, s5, s2
	s_sub_i32 s4, s4, s6
	s_add_i32 s6, s5, 1
	s_sub_i32 s7, s4, s2
	s_cmp_ge_u32 s4, s2
	s_cselect_b32 s5, s6, s5
	s_cselect_b32 s4, s7, s4
	s_add_i32 s6, s5, 1
	s_cmp_ge_u32 s4, s2
	s_cselect_b32 s4, s6, s5
	s_xor_b32 s4, s4, s0
	s_sub_i32 s0, s4, s0
	s_mul_i32 s2, s2, s0
	s_sub_i32 s2, s3, s2
	s_add_i32 s1, s1, s11
	s_add_i32 s2, s1, s2
	v_ashrrev_i32_e32 v233, 6, v181
	v_lshlrev_b32_e32 v0, 1, v233
	v_lshl_add_u32 v0, s2, 3, v0
	v_ashrrev_i32_e32 v1, 31, v0
	v_bfe_u32 v183, v181, 5, 1
	v_lshlrev_b64 v[0:1], 16, v[0:1]
	v_and_b32_e32 v231, 31, v181
	v_lshl_add_u64 v[0:1], s[64:65], 0, v[0:1]
	v_lshlrev_b32_e32 v176, 9, v183
	s_ashr_i32 s1, s0, 31
	v_lshl_add_u64 v[0:1], v[0:1], 0, v[176:177]
	v_lshlrev_b32_e32 v176, 4, v231
	v_ashrrev_i32_e32 v12, 2, v181
	s_lshl_b64 s[4:5], s[0:1], 18
	v_lshl_add_u64 v[184:185], v[0:1], 0, v[176:177]
	s_add_u32 s4, s9, s4
	v_lshlrev_b32_e32 v0, 5, v12
	s_addc_u32 s5, s10, s5
	v_ashrrev_i32_e32 v1, 31, v0
	v_lshlrev_b32_e32 v2, 4, v181
	v_lshl_add_u64 v[0:1], v[0:1], 1, s[4:5]
	v_and_b32_e32 v176, 48, v2
	v_lshl_add_u64 v[186:187], v[0:1], 0, v[176:177]
	s_movk_i32 s1, 0x2000
	v_add_co_u32_e32 v8, vcc, s1, v186
	v_mul_u32_u24_e32 v10, 40, v231
	s_nop 0
	v_addc_co_u32_e32 v9, vcc, 0, v187, vcc
	v_lshlrev_b32_e32 v11, 4, v183
	v_lshl_add_u32 v235, v10, 1, v11
	v_add_co_u32_e32 v10, vcc, s41, v184
	s_movk_i32 s3, 0x50
	s_nop 0
	v_addc_co_u32_e32 v11, vcc, 0, v185, vcc
	v_and_b32_e32 v232, 63, v181
	v_lshlrev_b32_e32 v234, 3, v181
	v_bfe_u32 v197, v181, 4, 2
	v_lshlrev_b32_e32 v197, 1, v197
	v_mov_b32_e32 v176, 0x78
	v_lshrrev_b32_e32 v197, v197, v176
	v_and_b32_e32 v197, 3, v197
	v_and_b32_e32 v196, 3, v181
	v_xor_b32_e32 v197, v197, v196
	v_lshlrev_b32_e32 v197, 4, v197
	v_and_b32_e32 v188, 0xffffffcf, v186
	v_or_b32_e32 v188, v188, v197
	v_mov_b32_e32 v189, v187
	v_lshrrev_b32_e32 v176, 6, v181
	v_lshlrev_b32_e32 v197, 11, v176
	v_lshlrev_b32_e32 v176, 10, v176
	v_lshl_add_u64 v[188:189], v[188:189], 0, v[176:177]
	v_readfirstlane_b32 vcc_lo, v197
	v_bfe_u32 v197, v181, 4, 1
	v_lshlrev_b32_e32 v176, 9, v183
	v_lshl_add_u32 v176, v197, 8, v176
	v_lshl_add_u64 v[184:185], v[184:185], 0, v[176:177]
	v_mov_b32_e32 v176, s41
	v_lshl_add_u64 v[186:187], v[184:185], 0, v[176:177]
	v_mov_b32_e32 v176, 0x78
	v_bfe_u32 v197, v181, 2, 1
	v_lshlrev_b32_e32 v197, 2, v197
	v_lshrrev_b32_e32 v197, v197, v176
	v_and_b32_e32 v197, 3, v197
	v_bfe_u32 v196, v181, 4, 2
	v_xor_b32_e32 v197, v197, v196
	v_lshlrev_b32_e32 v197, 4, v197
	v_bfe_u32 v196, v181, 2, 2
	v_lshlrev_b32_e32 v196, 3, v196
	v_and_b32_e32 v162, 3, v181
	v_add_u32_e32 v196, v196, v162
	v_lshl_add_u32 v196, v196, 6, v197
	v_bfe_u32 v197, v181, 2, 1
	v_lshlrev_b32_e32 v197, 2, v197
	v_add_u32_e32 v197, 2, v197
	v_lshrrev_b32_e32 v197, v197, v176
	v_and_b32_e32 v197, 3, v197
	v_bfe_u32 v162, v181, 4, 2
	v_xor_b32_e32 v197, v197, v162
	v_lshlrev_b32_e32 v197, 4, v197
	v_and_b32_e32 v162, 0xffffffcf, v196
	v_add_u32_e32 v162, 0x100, v162
	v_or_b32_e32 v162, v162, v197
	s_mov_b32 s96, 0
	s_mov_b32 m0, vcc_lo
	v_lshl_add_u64 v[160:161], v[188:189], 0, s[96:97]
	global_load_lds_dwordx4 v[160:161], off
	global_load_lds_dwordx4 v[160:161], off offset:1024
	s_mov_b32 s96, 0
	v_lshl_add_u64 v[198:199], v[184:185], 0, s[96:97]
	v_lshl_add_u64 v[200:201], v[186:187], 0, s[96:97]
	global_load_dwordx4 v[128:131], v[198:199], off
	global_load_dwordx4 v[132:135], v[198:199], off offset:256
	global_load_dwordx4 v[136:139], v[200:201], off
	global_load_dwordx4 v[140:143], v[200:201], off offset:256
	s_movk_i32 s96, 0x2000
	s_add_i32 m0, vcc_lo, 8192
	v_lshl_add_u64 v[160:161], v[188:189], 0, s[96:97]
	global_load_lds_dwordx4 v[160:161], off
	global_load_lds_dwordx4 v[160:161], off offset:1024
	s_movk_i32 s96, 0x800
	v_lshl_add_u64 v[198:199], v[184:185], 0, s[96:97]
	v_lshl_add_u64 v[200:201], v[186:187], 0, s[96:97]
	global_load_dwordx4 v[144:147], v[198:199], off
	global_load_dwordx4 v[148:151], v[198:199], off offset:256
	global_load_dwordx4 v[152:155], v[200:201], off
	global_load_dwordx4 v[156:159], v[200:201], off offset:256
	v_mov_b32_e32 v0, 0
	v_mov_b32_e32 v1, 0
	v_mov_b32_e32 v2, 0
	v_mov_b32_e32 v3, 0
	v_mov_b32_e32 v4, 0
	v_mov_b32_e32 v5, 0
	v_mov_b32_e32 v6, 0
	v_mov_b32_e32 v7, 0
	v_mov_b32_e32 v8, 0
	v_mov_b32_e32 v9, 0
	v_mov_b32_e32 v10, 0
	v_mov_b32_e32 v11, 0
	v_mov_b32_e32 v12, 0
	v_mov_b32_e32 v13, 0
	v_mov_b32_e32 v14, 0
	v_mov_b32_e32 v15, 0
	v_mov_b32_e32 v16, 0
	v_mov_b32_e32 v17, 0
	v_mov_b32_e32 v18, 0
	v_mov_b32_e32 v19, 0
	v_mov_b32_e32 v20, 0
	v_mov_b32_e32 v21, 0
	v_mov_b32_e32 v22, 0
	v_mov_b32_e32 v23, 0
	v_mov_b32_e32 v24, 0
	v_mov_b32_e32 v25, 0
	v_mov_b32_e32 v26, 0
	v_mov_b32_e32 v27, 0
	v_mov_b32_e32 v28, 0
	v_mov_b32_e32 v29, 0
	v_mov_b32_e32 v30, 0
	v_mov_b32_e32 v31, 0
	v_mov_b32_e32 v32, 0
	v_mov_b32_e32 v33, 0
	v_mov_b32_e32 v34, 0
	v_mov_b32_e32 v35, 0
	v_mov_b32_e32 v36, 0
	v_mov_b32_e32 v37, 0
	v_mov_b32_e32 v38, 0
	v_mov_b32_e32 v39, 0
	v_mov_b32_e32 v40, 0
	v_mov_b32_e32 v41, 0
	v_mov_b32_e32 v42, 0
	v_mov_b32_e32 v43, 0
	v_mov_b32_e32 v44, 0
	v_mov_b32_e32 v45, 0
	v_mov_b32_e32 v46, 0
	v_mov_b32_e32 v47, 0
	v_mov_b32_e32 v48, 0
	v_mov_b32_e32 v49, 0
	v_mov_b32_e32 v50, 0
	v_mov_b32_e32 v51, 0
	v_mov_b32_e32 v52, 0
	v_mov_b32_e32 v53, 0
	v_mov_b32_e32 v54, 0
	v_mov_b32_e32 v55, 0
	v_mov_b32_e32 v56, 0
	v_mov_b32_e32 v57, 0
	v_mov_b32_e32 v58, 0
	v_mov_b32_e32 v59, 0
	v_mov_b32_e32 v60, 0
	v_mov_b32_e32 v61, 0
	v_mov_b32_e32 v62, 0
	v_mov_b32_e32 v63, 0
	v_mov_b32_e32 v64, 0
	v_mov_b32_e32 v65, 0
	v_mov_b32_e32 v66, 0
	v_mov_b32_e32 v67, 0
	v_mov_b32_e32 v68, 0
	v_mov_b32_e32 v69, 0
	v_mov_b32_e32 v70, 0
	v_mov_b32_e32 v71, 0
	v_mov_b32_e32 v72, 0
	v_mov_b32_e32 v73, 0
	v_mov_b32_e32 v74, 0
	v_mov_b32_e32 v75, 0
	v_mov_b32_e32 v76, 0
	v_mov_b32_e32 v77, 0
	v_mov_b32_e32 v78, 0
	v_mov_b32_e32 v79, 0
	v_mov_b32_e32 v80, 0
	v_mov_b32_e32 v81, 0
	v_mov_b32_e32 v82, 0
	v_mov_b32_e32 v83, 0
	v_mov_b32_e32 v84, 0
	v_mov_b32_e32 v85, 0
	v_mov_b32_e32 v86, 0
	v_mov_b32_e32 v87, 0
	v_mov_b32_e32 v88, 0
	v_mov_b32_e32 v89, 0
	v_mov_b32_e32 v90, 0
	v_mov_b32_e32 v91, 0
	v_mov_b32_e32 v92, 0
	v_mov_b32_e32 v93, 0
	v_mov_b32_e32 v94, 0
	v_mov_b32_e32 v95, 0
	v_mov_b32_e32 v96, 0
	v_mov_b32_e32 v97, 0
	v_mov_b32_e32 v98, 0
	v_mov_b32_e32 v99, 0
	v_mov_b32_e32 v100, 0
	v_mov_b32_e32 v101, 0
	v_mov_b32_e32 v102, 0
	v_mov_b32_e32 v103, 0
	v_mov_b32_e32 v104, 0
	v_mov_b32_e32 v105, 0
	v_mov_b32_e32 v106, 0
	v_mov_b32_e32 v107, 0
	v_mov_b32_e32 v108, 0
	v_mov_b32_e32 v109, 0
	v_mov_b32_e32 v110, 0
	v_mov_b32_e32 v111, 0
	v_mov_b32_e32 v112, 0
	v_mov_b32_e32 v113, 0
	v_mov_b32_e32 v114, 0
	v_mov_b32_e32 v115, 0
	v_mov_b32_e32 v116, 0
	v_mov_b32_e32 v117, 0
	v_mov_b32_e32 v118, 0
	v_mov_b32_e32 v119, 0
	v_mov_b32_e32 v120, 0
	v_mov_b32_e32 v121, 0
	v_mov_b32_e32 v122, 0
	v_mov_b32_e32 v123, 0
	v_mov_b32_e32 v124, 0
	v_mov_b32_e32 v125, 0
	v_mov_b32_e32 v126, 0
	v_mov_b32_e32 v127, 0
	s_mov_b32 s1, 0
	s_waitcnt vmcnt(4)
	s_barrier
.Lg16_proj_k:
	s_add_i32 s3, s1, 2
	s_lshl_b32 s96, s3, 13
	s_add_i32 m0, vcc_lo, 16384
	v_lshl_add_u64 v[160:161], v[188:189], 0, s[96:97]
	global_load_lds_dwordx4 v[160:161], off
	global_load_lds_dwordx4 v[160:161], off offset:1024
	ds_read_b128 v[236:239], v196 offset:0
	ds_read_b128 v[240:243], v162 offset:0
	ds_read_b128 v[244:247], v196 offset:2048
	ds_read_b128 v[248:251], v162 offset:2048
	s_add_i32 s3, s1, 2
	s_lshl_b32 s96, s3, 11
	v_lshl_add_u64 v[198:199], v[184:185], 0, s[96:97]
	v_lshl_add_u64 v[200:201], v[186:187], 0, s[96:97]
	s_waitcnt vmcnt(8) lgkmcnt(3)
	v_mfma_f32_16x16x32_bf16 v[16:19], v[236:239], v[128:131], v[16:19]
	v_mfma_f32_16x16x32_bf16 v[24:27], v[236:239], v[132:135], v[24:27]
	v_mfma_f32_16x16x32_bf16 v[0:3], v[236:239], v[136:139], v[0:3]
	v_mfma_f32_16x16x32_bf16 v[8:11], v[236:239], v[140:143], v[8:11]
	ds_read_b128 v[236:239], v196 offset:4096
	s_waitcnt lgkmcnt(3)
	v_mfma_f32_16x16x32_bf16 v[20:23], v[240:243], v[128:131], v[20:23]
	v_mfma_f32_16x16x32_bf16 v[28:31], v[240:243], v[132:135], v[28:31]
	v_mfma_f32_16x16x32_bf16 v[4:7], v[240:243], v[136:139], v[4:7]
	v_mfma_f32_16x16x32_bf16 v[12:15], v[240:243], v[140:143], v[12:15]
	ds_read_b128 v[240:243], v162 offset:4096
	s_waitcnt lgkmcnt(3)
	v_mfma_f32_16x16x32_bf16 v[112:115], v[244:247], v[128:131], v[112:115]
	v_mfma_f32_16x16x32_bf16 v[120:123], v[244:247], v[132:135], v[120:123]
	v_mfma_f32_16x16x32_bf16 v[96:99], v[244:247], v[136:139], v[96:99]
	v_mfma_f32_16x16x32_bf16 v[104:107], v[244:247], v[140:143], v[104:107]
	ds_read_b128 v[244:247], v196 offset:6144
	s_waitcnt lgkmcnt(3)
	v_mfma_f32_16x16x32_bf16 v[116:119], v[248:251], v[128:131], v[116:119]
	v_mfma_f32_16x16x32_bf16 v[124:127], v[248:251], v[132:135], v[124:127]
	v_mfma_f32_16x16x32_bf16 v[100:103], v[248:251], v[136:139], v[100:103]
	v_mfma_f32_16x16x32_bf16 v[108:111], v[248:251], v[140:143], v[108:111]
	ds_read_b128 v[248:251], v162 offset:6144
	s_waitcnt lgkmcnt(3)
	v_mfma_f32_16x16x32_bf16 v[80:83], v[236:239], v[128:131], v[80:83]
	v_mfma_f32_16x16x32_bf16 v[88:91], v[236:239], v[132:135], v[88:91]
	v_mfma_f32_16x16x32_bf16 v[48:51], v[236:239], v[136:139], v[48:51]
	v_mfma_f32_16x16x32_bf16 v[56:59], v[236:239], v[140:143], v[56:59]
	s_waitcnt lgkmcnt(2)
	v_mfma_f32_16x16x32_bf16 v[84:87], v[240:243], v[128:131], v[84:87]
	v_mfma_f32_16x16x32_bf16 v[92:95], v[240:243], v[132:135], v[92:95]
	v_mfma_f32_16x16x32_bf16 v[52:55], v[240:243], v[136:139], v[52:55]
	v_mfma_f32_16x16x32_bf16 v[60:63], v[240:243], v[140:143], v[60:63]
	s_waitcnt lgkmcnt(1)
	v_mfma_f32_16x16x32_bf16 v[64:67], v[244:247], v[128:131], v[64:67]
	v_mfma_f32_16x16x32_bf16 v[72:75], v[244:247], v[132:135], v[72:75]
	v_mfma_f32_16x16x32_bf16 v[32:35], v[244:247], v[136:139], v[32:35]
	v_mfma_f32_16x16x32_bf16 v[40:43], v[244:247], v[140:143], v[40:43]
	s_waitcnt lgkmcnt(0)
	v_mfma_f32_16x16x32_bf16 v[68:71], v[248:251], v[128:131], v[68:71]
	v_mfma_f32_16x16x32_bf16 v[76:79], v[248:251], v[132:135], v[76:79]
	v_mfma_f32_16x16x32_bf16 v[36:39], v[248:251], v[136:139], v[36:39]
	v_mfma_f32_16x16x32_bf16 v[44:47], v[248:251], v[140:143], v[44:47]
	global_load_dwordx4 v[128:131], v[198:199], off
	global_load_dwordx4 v[132:135], v[198:199], off offset:256
	global_load_dwordx4 v[136:139], v[200:201], off
	global_load_dwordx4 v[140:143], v[200:201], off offset:256
	s_waitcnt vmcnt(10)
	s_barrier
	s_add_i32 s3, s1, 3
	s_lshl_b32 s96, s3, 13
	s_mov_b32 m0, vcc_lo
	v_lshl_add_u64 v[160:161], v[188:189], 0, s[96:97]
	global_load_lds_dwordx4 v[160:161], off
	global_load_lds_dwordx4 v[160:161], off offset:1024
	ds_read_b128 v[236:239], v196 offset:8192
	ds_read_b128 v[240:243], v162 offset:8192
	ds_read_b128 v[244:247], v196 offset:10240
	ds_read_b128 v[248:251], v162 offset:10240
	s_add_i32 s3, s1, 3
	s_lshl_b32 s96, s3, 11
	v_lshl_add_u64 v[198:199], v[184:185], 0, s[96:97]
	v_lshl_add_u64 v[200:201], v[186:187], 0, s[96:97]
	s_waitcnt vmcnt(8) lgkmcnt(3)
	v_mfma_f32_16x16x32_bf16 v[16:19], v[236:239], v[144:147], v[16:19]
	v_mfma_f32_16x16x32_bf16 v[24:27], v[236:239], v[148:151], v[24:27]
	v_mfma_f32_16x16x32_bf16 v[0:3], v[236:239], v[152:155], v[0:3]
	v_mfma_f32_16x16x32_bf16 v[8:11], v[236:239], v[156:159], v[8:11]
	ds_read_b128 v[236:239], v196 offset:12288
	s_waitcnt lgkmcnt(3)
	v_mfma_f32_16x16x32_bf16 v[20:23], v[240:243], v[144:147], v[20:23]
	v_mfma_f32_16x16x32_bf16 v[28:31], v[240:243], v[148:151], v[28:31]
	v_mfma_f32_16x16x32_bf16 v[4:7], v[240:243], v[152:155], v[4:7]
	v_mfma_f32_16x16x32_bf16 v[12:15], v[240:243], v[156:159], v[12:15]
	ds_read_b128 v[240:243], v162 offset:12288
	s_waitcnt lgkmcnt(3)
	v_mfma_f32_16x16x32_bf16 v[112:115], v[244:247], v[144:147], v[112:115]
	v_mfma_f32_16x16x32_bf16 v[120:123], v[244:247], v[148:151], v[120:123]
	v_mfma_f32_16x16x32_bf16 v[96:99], v[244:247], v[152:155], v[96:99]
	v_mfma_f32_16x16x32_bf16 v[104:107], v[244:247], v[156:159], v[104:107]
	ds_read_b128 v[244:247], v196 offset:14336
	s_waitcnt lgkmcnt(3)
	v_mfma_f32_16x16x32_bf16 v[116:119], v[248:251], v[144:147], v[116:119]
	v_mfma_f32_16x16x32_bf16 v[124:127], v[248:251], v[148:151], v[124:127]
	v_mfma_f32_16x16x32_bf16 v[100:103], v[248:251], v[152:155], v[100:103]
	v_mfma_f32_16x16x32_bf16 v[108:111], v[248:251], v[156:159], v[108:111]
	ds_read_b128 v[248:251], v162 offset:14336
	s_waitcnt lgkmcnt(3)
	v_mfma_f32_16x16x32_bf16 v[80:83], v[236:239], v[144:147], v[80:83]
	v_mfma_f32_16x16x32_bf16 v[88:91], v[236:239], v[148:151], v[88:91]
	v_mfma_f32_16x16x32_bf16 v[48:51], v[236:239], v[152:155], v[48:51]
	v_mfma_f32_16x16x32_bf16 v[56:59], v[236:239], v[156:159], v[56:59]
	s_waitcnt lgkmcnt(2)
	v_mfma_f32_16x16x32_bf16 v[84:87], v[240:243], v[144:147], v[84:87]
	v_mfma_f32_16x16x32_bf16 v[92:95], v[240:243], v[148:151], v[92:95]
	v_mfma_f32_16x16x32_bf16 v[52:55], v[240:243], v[152:155], v[52:55]
	v_mfma_f32_16x16x32_bf16 v[60:63], v[240:243], v[156:159], v[60:63]
	s_waitcnt lgkmcnt(1)
	v_mfma_f32_16x16x32_bf16 v[64:67], v[244:247], v[144:147], v[64:67]
	v_mfma_f32_16x16x32_bf16 v[72:75], v[244:247], v[148:151], v[72:75]
	v_mfma_f32_16x16x32_bf16 v[32:35], v[244:247], v[152:155], v[32:35]
	v_mfma_f32_16x16x32_bf16 v[40:43], v[244:247], v[156:159], v[40:43]
	s_waitcnt lgkmcnt(0)
	v_mfma_f32_16x16x32_bf16 v[68:71], v[248:251], v[144:147], v[68:71]
	v_mfma_f32_16x16x32_bf16 v[76:79], v[248:251], v[148:151], v[76:79]
	v_mfma_f32_16x16x32_bf16 v[36:39], v[248:251], v[152:155], v[36:39]
	v_mfma_f32_16x16x32_bf16 v[44:47], v[248:251], v[156:159], v[44:47]
	global_load_dwordx4 v[144:147], v[198:199], off
	global_load_dwordx4 v[148:151], v[198:199], off offset:256
	global_load_dwordx4 v[152:155], v[200:201], off
	global_load_dwordx4 v[156:159], v[200:201], off offset:256
	s_waitcnt vmcnt(10)
	s_barrier
	s_add_i32 s3, s1, 4
	s_lshl_b32 s96, s3, 13
	s_add_i32 m0, vcc_lo, 8192
	v_lshl_add_u64 v[160:161], v[188:189], 0, s[96:97]
	global_load_lds_dwordx4 v[160:161], off
	global_load_lds_dwordx4 v[160:161], off offset:1024
	ds_read_b128 v[236:239], v196 offset:16384
	ds_read_b128 v[240:243], v162 offset:16384
	ds_read_b128 v[244:247], v196 offset:18432
	ds_read_b128 v[248:251], v162 offset:18432
	s_add_i32 s3, s1, 4
	s_lshl_b32 s96, s3, 11
	v_lshl_add_u64 v[198:199], v[184:185], 0, s[96:97]
	v_lshl_add_u64 v[200:201], v[186:187], 0, s[96:97]
	s_waitcnt vmcnt(8) lgkmcnt(3)
	v_mfma_f32_16x16x32_bf16 v[16:19], v[236:239], v[128:131], v[16:19]
	v_mfma_f32_16x16x32_bf16 v[24:27], v[236:239], v[132:135], v[24:27]
	v_mfma_f32_16x16x32_bf16 v[0:3], v[236:239], v[136:139], v[0:3]
	v_mfma_f32_16x16x32_bf16 v[8:11], v[236:239], v[140:143], v[8:11]
	ds_read_b128 v[236:239], v196 offset:20480
	s_waitcnt lgkmcnt(3)
	v_mfma_f32_16x16x32_bf16 v[20:23], v[240:243], v[128:131], v[20:23]
	v_mfma_f32_16x16x32_bf16 v[28:31], v[240:243], v[132:135], v[28:31]
	v_mfma_f32_16x16x32_bf16 v[4:7], v[240:243], v[136:139], v[4:7]
	v_mfma_f32_16x16x32_bf16 v[12:15], v[240:243], v[140:143], v[12:15]
	ds_read_b128 v[240:243], v162 offset:20480
	s_waitcnt lgkmcnt(3)
	v_mfma_f32_16x16x32_bf16 v[112:115], v[244:247], v[128:131], v[112:115]
	v_mfma_f32_16x16x32_bf16 v[120:123], v[244:247], v[132:135], v[120:123]
	v_mfma_f32_16x16x32_bf16 v[96:99], v[244:247], v[136:139], v[96:99]
	v_mfma_f32_16x16x32_bf16 v[104:107], v[244:247], v[140:143], v[104:107]
	ds_read_b128 v[244:247], v196 offset:22528
	s_waitcnt lgkmcnt(3)
	v_mfma_f32_16x16x32_bf16 v[116:119], v[248:251], v[128:131], v[116:119]
	v_mfma_f32_16x16x32_bf16 v[124:127], v[248:251], v[132:135], v[124:127]
	v_mfma_f32_16x16x32_bf16 v[100:103], v[248:251], v[136:139], v[100:103]
	v_mfma_f32_16x16x32_bf16 v[108:111], v[248:251], v[140:143], v[108:111]
	ds_read_b128 v[248:251], v162 offset:22528
	s_waitcnt lgkmcnt(3)
	v_mfma_f32_16x16x32_bf16 v[80:83], v[236:239], v[128:131], v[80:83]
	v_mfma_f32_16x16x32_bf16 v[88:91], v[236:239], v[132:135], v[88:91]
	v_mfma_f32_16x16x32_bf16 v[48:51], v[236:239], v[136:139], v[48:51]
	v_mfma_f32_16x16x32_bf16 v[56:59], v[236:239], v[140:143], v[56:59]
	s_waitcnt lgkmcnt(2)
	v_mfma_f32_16x16x32_bf16 v[84:87], v[240:243], v[128:131], v[84:87]
	v_mfma_f32_16x16x32_bf16 v[92:95], v[240:243], v[132:135], v[92:95]
	v_mfma_f32_16x16x32_bf16 v[52:55], v[240:243], v[136:139], v[52:55]
	v_mfma_f32_16x16x32_bf16 v[60:63], v[240:243], v[140:143], v[60:63]
	s_waitcnt lgkmcnt(1)
	v_mfma_f32_16x16x32_bf16 v[64:67], v[244:247], v[128:131], v[64:67]
	v_mfma_f32_16x16x32_bf16 v[72:75], v[244:247], v[132:135], v[72:75]
	v_mfma_f32_16x16x32_bf16 v[32:35], v[244:247], v[136:139], v[32:35]
	v_mfma_f32_16x16x32_bf16 v[40:43], v[244:247], v[140:143], v[40:43]
	s_waitcnt lgkmcnt(0)
	v_mfma_f32_16x16x32_bf16 v[68:71], v[248:251], v[128:131], v[68:71]
	v_mfma_f32_16x16x32_bf16 v[76:79], v[248:251], v[132:135], v[76:79]
	v_mfma_f32_16x16x32_bf16 v[36:39], v[248:251], v[136:139], v[36:39]
	v_mfma_f32_16x16x32_bf16 v[44:47], v[248:251], v[140:143], v[44:47]
	global_load_dwordx4 v[128:131], v[198:199], off
	global_load_dwordx4 v[132:135], v[198:199], off offset:256
	global_load_dwordx4 v[136:139], v[200:201], off
	global_load_dwordx4 v[140:143], v[200:201], off offset:256
	s_waitcnt vmcnt(10)
	s_barrier
	s_add_i32 s3, s1, 5
	s_lshl_b32 s96, s3, 13
	s_add_i32 m0, vcc_lo, 16384
	v_lshl_add_u64 v[160:161], v[188:189], 0, s[96:97]
	global_load_lds_dwordx4 v[160:161], off
	global_load_lds_dwordx4 v[160:161], off offset:1024
	ds_read_b128 v[236:239], v196 offset:0
	ds_read_b128 v[240:243], v162 offset:0
	ds_read_b128 v[244:247], v196 offset:2048
	ds_read_b128 v[248:251], v162 offset:2048
	s_add_i32 s3, s1, 5
	s_lshl_b32 s96, s3, 11
	v_lshl_add_u64 v[198:199], v[184:185], 0, s[96:97]
	v_lshl_add_u64 v[200:201], v[186:187], 0, s[96:97]
	s_waitcnt vmcnt(8) lgkmcnt(3)
	v_mfma_f32_16x16x32_bf16 v[16:19], v[236:239], v[144:147], v[16:19]
	v_mfma_f32_16x16x32_bf16 v[24:27], v[236:239], v[148:151], v[24:27]
	v_mfma_f32_16x16x32_bf16 v[0:3], v[236:239], v[152:155], v[0:3]
	v_mfma_f32_16x16x32_bf16 v[8:11], v[236:239], v[156:159], v[8:11]
	ds_read_b128 v[236:239], v196 offset:4096
	s_waitcnt lgkmcnt(3)
	v_mfma_f32_16x16x32_bf16 v[20:23], v[240:243], v[144:147], v[20:23]
	v_mfma_f32_16x16x32_bf16 v[28:31], v[240:243], v[148:151], v[28:31]
	v_mfma_f32_16x16x32_bf16 v[4:7], v[240:243], v[152:155], v[4:7]
	v_mfma_f32_16x16x32_bf16 v[12:15], v[240:243], v[156:159], v[12:15]
	ds_read_b128 v[240:243], v162 offset:4096
	s_waitcnt lgkmcnt(3)
	v_mfma_f32_16x16x32_bf16 v[112:115], v[244:247], v[144:147], v[112:115]
	v_mfma_f32_16x16x32_bf16 v[120:123], v[244:247], v[148:151], v[120:123]
	v_mfma_f32_16x16x32_bf16 v[96:99], v[244:247], v[152:155], v[96:99]
	v_mfma_f32_16x16x32_bf16 v[104:107], v[244:247], v[156:159], v[104:107]
	ds_read_b128 v[244:247], v196 offset:6144
	s_waitcnt lgkmcnt(3)
	v_mfma_f32_16x16x32_bf16 v[116:119], v[248:251], v[144:147], v[116:119]
	v_mfma_f32_16x16x32_bf16 v[124:127], v[248:251], v[148:151], v[124:127]
	v_mfma_f32_16x16x32_bf16 v[100:103], v[248:251], v[152:155], v[100:103]
	v_mfma_f32_16x16x32_bf16 v[108:111], v[248:251], v[156:159], v[108:111]
	ds_read_b128 v[248:251], v162 offset:6144
	s_waitcnt lgkmcnt(3)
	v_mfma_f32_16x16x32_bf16 v[80:83], v[236:239], v[144:147], v[80:83]
	v_mfma_f32_16x16x32_bf16 v[88:91], v[236:239], v[148:151], v[88:91]
	v_mfma_f32_16x16x32_bf16 v[48:51], v[236:239], v[152:155], v[48:51]
	v_mfma_f32_16x16x32_bf16 v[56:59], v[236:239], v[156:159], v[56:59]
	s_waitcnt lgkmcnt(2)
	v_mfma_f32_16x16x32_bf16 v[84:87], v[240:243], v[144:147], v[84:87]
	v_mfma_f32_16x16x32_bf16 v[92:95], v[240:243], v[148:151], v[92:95]
	v_mfma_f32_16x16x32_bf16 v[52:55], v[240:243], v[152:155], v[52:55]
	v_mfma_f32_16x16x32_bf16 v[60:63], v[240:243], v[156:159], v[60:63]
	s_waitcnt lgkmcnt(1)
	v_mfma_f32_16x16x32_bf16 v[64:67], v[244:247], v[144:147], v[64:67]
	v_mfma_f32_16x16x32_bf16 v[72:75], v[244:247], v[148:151], v[72:75]
	v_mfma_f32_16x16x32_bf16 v[32:35], v[244:247], v[152:155], v[32:35]
	v_mfma_f32_16x16x32_bf16 v[40:43], v[244:247], v[156:159], v[40:43]
	s_waitcnt lgkmcnt(0)
	v_mfma_f32_16x16x32_bf16 v[68:71], v[248:251], v[144:147], v[68:71]
	v_mfma_f32_16x16x32_bf16 v[76:79], v[248:251], v[148:151], v[76:79]
	v_mfma_f32_16x16x32_bf16 v[36:39], v[248:251], v[152:155], v[36:39]
	v_mfma_f32_16x16x32_bf16 v[44:47], v[248:251], v[156:159], v[44:47]
	global_load_dwordx4 v[144:147], v[198:199], off
	global_load_dwordx4 v[148:151], v[198:199], off offset:256
	global_load_dwordx4 v[152:155], v[200:201], off
	global_load_dwordx4 v[156:159], v[200:201], off offset:256
	s_waitcnt vmcnt(10)
	s_barrier
	s_add_i32 s3, s1, 6
	s_lshl_b32 s96, s3, 13
	s_mov_b32 m0, vcc_lo
	v_lshl_add_u64 v[160:161], v[188:189], 0, s[96:97]
	global_load_lds_dwordx4 v[160:161], off
	global_load_lds_dwordx4 v[160:161], off offset:1024
	ds_read_b128 v[236:239], v196 offset:8192
	ds_read_b128 v[240:243], v162 offset:8192
	ds_read_b128 v[244:247], v196 offset:10240
	ds_read_b128 v[248:251], v162 offset:10240
	s_add_i32 s3, s1, 6
	s_lshl_b32 s96, s3, 11
	v_lshl_add_u64 v[198:199], v[184:185], 0, s[96:97]
	v_lshl_add_u64 v[200:201], v[186:187], 0, s[96:97]
	s_waitcnt vmcnt(8) lgkmcnt(3)
	v_mfma_f32_16x16x32_bf16 v[16:19], v[236:239], v[128:131], v[16:19]
	v_mfma_f32_16x16x32_bf16 v[24:27], v[236:239], v[132:135], v[24:27]
	v_mfma_f32_16x16x32_bf16 v[0:3], v[236:239], v[136:139], v[0:3]
	v_mfma_f32_16x16x32_bf16 v[8:11], v[236:239], v[140:143], v[8:11]
	ds_read_b128 v[236:239], v196 offset:12288
	s_waitcnt lgkmcnt(3)
	v_mfma_f32_16x16x32_bf16 v[20:23], v[240:243], v[128:131], v[20:23]
	v_mfma_f32_16x16x32_bf16 v[28:31], v[240:243], v[132:135], v[28:31]
	v_mfma_f32_16x16x32_bf16 v[4:7], v[240:243], v[136:139], v[4:7]
	v_mfma_f32_16x16x32_bf16 v[12:15], v[240:243], v[140:143], v[12:15]
	ds_read_b128 v[240:243], v162 offset:12288
	s_waitcnt lgkmcnt(3)
	v_mfma_f32_16x16x32_bf16 v[112:115], v[244:247], v[128:131], v[112:115]
	v_mfma_f32_16x16x32_bf16 v[120:123], v[244:247], v[132:135], v[120:123]
	v_mfma_f32_16x16x32_bf16 v[96:99], v[244:247], v[136:139], v[96:99]
	v_mfma_f32_16x16x32_bf16 v[104:107], v[244:247], v[140:143], v[104:107]
	ds_read_b128 v[244:247], v196 offset:14336
	s_waitcnt lgkmcnt(3)
	v_mfma_f32_16x16x32_bf16 v[116:119], v[248:251], v[128:131], v[116:119]
	v_mfma_f32_16x16x32_bf16 v[124:127], v[248:251], v[132:135], v[124:127]
	v_mfma_f32_16x16x32_bf16 v[100:103], v[248:251], v[136:139], v[100:103]
	v_mfma_f32_16x16x32_bf16 v[108:111], v[248:251], v[140:143], v[108:111]
	ds_read_b128 v[248:251], v162 offset:14336
	s_waitcnt lgkmcnt(3)
	v_mfma_f32_16x16x32_bf16 v[80:83], v[236:239], v[128:131], v[80:83]
	v_mfma_f32_16x16x32_bf16 v[88:91], v[236:239], v[132:135], v[88:91]
	v_mfma_f32_16x16x32_bf16 v[48:51], v[236:239], v[136:139], v[48:51]
	v_mfma_f32_16x16x32_bf16 v[56:59], v[236:239], v[140:143], v[56:59]
	s_waitcnt lgkmcnt(2)
	v_mfma_f32_16x16x32_bf16 v[84:87], v[240:243], v[128:131], v[84:87]
	v_mfma_f32_16x16x32_bf16 v[92:95], v[240:243], v[132:135], v[92:95]
	v_mfma_f32_16x16x32_bf16 v[52:55], v[240:243], v[136:139], v[52:55]
	v_mfma_f32_16x16x32_bf16 v[60:63], v[240:243], v[140:143], v[60:63]
	s_waitcnt lgkmcnt(1)
	v_mfma_f32_16x16x32_bf16 v[64:67], v[244:247], v[128:131], v[64:67]
	v_mfma_f32_16x16x32_bf16 v[72:75], v[244:247], v[132:135], v[72:75]
	v_mfma_f32_16x16x32_bf16 v[32:35], v[244:247], v[136:139], v[32:35]
	v_mfma_f32_16x16x32_bf16 v[40:43], v[244:247], v[140:143], v[40:43]
	s_waitcnt lgkmcnt(0)
	v_mfma_f32_16x16x32_bf16 v[68:71], v[248:251], v[128:131], v[68:71]
	v_mfma_f32_16x16x32_bf16 v[76:79], v[248:251], v[132:135], v[76:79]
	v_mfma_f32_16x16x32_bf16 v[36:39], v[248:251], v[136:139], v[36:39]
	v_mfma_f32_16x16x32_bf16 v[44:47], v[248:251], v[140:143], v[44:47]
	global_load_dwordx4 v[128:131], v[198:199], off
	global_load_dwordx4 v[132:135], v[198:199], off offset:256
	global_load_dwordx4 v[136:139], v[200:201], off
	global_load_dwordx4 v[140:143], v[200:201], off offset:256
	s_waitcnt vmcnt(10)
	s_barrier
	s_add_i32 s3, s1, 7
	s_lshl_b32 s96, s3, 13
	s_add_i32 m0, vcc_lo, 8192
	v_lshl_add_u64 v[160:161], v[188:189], 0, s[96:97]
	global_load_lds_dwordx4 v[160:161], off
	global_load_lds_dwordx4 v[160:161], off offset:1024
	ds_read_b128 v[236:239], v196 offset:16384
	ds_read_b128 v[240:243], v162 offset:16384
	ds_read_b128 v[244:247], v196 offset:18432
	ds_read_b128 v[248:251], v162 offset:18432
	s_add_i32 s3, s1, 7
	s_lshl_b32 s96, s3, 11
	v_lshl_add_u64 v[198:199], v[184:185], 0, s[96:97]
	v_lshl_add_u64 v[200:201], v[186:187], 0, s[96:97]
	s_waitcnt vmcnt(8) lgkmcnt(3)
	v_mfma_f32_16x16x32_bf16 v[16:19], v[236:239], v[144:147], v[16:19]
	v_mfma_f32_16x16x32_bf16 v[24:27], v[236:239], v[148:151], v[24:27]
	v_mfma_f32_16x16x32_bf16 v[0:3], v[236:239], v[152:155], v[0:3]
	v_mfma_f32_16x16x32_bf16 v[8:11], v[236:239], v[156:159], v[8:11]
	ds_read_b128 v[236:239], v196 offset:20480
	s_waitcnt lgkmcnt(3)
	v_mfma_f32_16x16x32_bf16 v[20:23], v[240:243], v[144:147], v[20:23]
	v_mfma_f32_16x16x32_bf16 v[28:31], v[240:243], v[148:151], v[28:31]
	v_mfma_f32_16x16x32_bf16 v[4:7], v[240:243], v[152:155], v[4:7]
	v_mfma_f32_16x16x32_bf16 v[12:15], v[240:243], v[156:159], v[12:15]
	ds_read_b128 v[240:243], v162 offset:20480
	s_waitcnt lgkmcnt(3)
	v_mfma_f32_16x16x32_bf16 v[112:115], v[244:247], v[144:147], v[112:115]
	v_mfma_f32_16x16x32_bf16 v[120:123], v[244:247], v[148:151], v[120:123]
	v_mfma_f32_16x16x32_bf16 v[96:99], v[244:247], v[152:155], v[96:99]
	v_mfma_f32_16x16x32_bf16 v[104:107], v[244:247], v[156:159], v[104:107]
	ds_read_b128 v[244:247], v196 offset:22528
	s_waitcnt lgkmcnt(3)
	v_mfma_f32_16x16x32_bf16 v[116:119], v[248:251], v[144:147], v[116:119]
	v_mfma_f32_16x16x32_bf16 v[124:127], v[248:251], v[148:151], v[124:127]
	v_mfma_f32_16x16x32_bf16 v[100:103], v[248:251], v[152:155], v[100:103]
	v_mfma_f32_16x16x32_bf16 v[108:111], v[248:251], v[156:159], v[108:111]
	ds_read_b128 v[248:251], v162 offset:22528
	s_waitcnt lgkmcnt(3)
	v_mfma_f32_16x16x32_bf16 v[80:83], v[236:239], v[144:147], v[80:83]
	v_mfma_f32_16x16x32_bf16 v[88:91], v[236:239], v[148:151], v[88:91]
	v_mfma_f32_16x16x32_bf16 v[48:51], v[236:239], v[152:155], v[48:51]
	v_mfma_f32_16x16x32_bf16 v[56:59], v[236:239], v[156:159], v[56:59]
	s_waitcnt lgkmcnt(2)
	v_mfma_f32_16x16x32_bf16 v[84:87], v[240:243], v[144:147], v[84:87]
	v_mfma_f32_16x16x32_bf16 v[92:95], v[240:243], v[148:151], v[92:95]
	v_mfma_f32_16x16x32_bf16 v[52:55], v[240:243], v[152:155], v[52:55]
	v_mfma_f32_16x16x32_bf16 v[60:63], v[240:243], v[156:159], v[60:63]
	s_waitcnt lgkmcnt(1)
	v_mfma_f32_16x16x32_bf16 v[64:67], v[244:247], v[144:147], v[64:67]
	v_mfma_f32_16x16x32_bf16 v[72:75], v[244:247], v[148:151], v[72:75]
	v_mfma_f32_16x16x32_bf16 v[32:35], v[244:247], v[152:155], v[32:35]
	v_mfma_f32_16x16x32_bf16 v[40:43], v[244:247], v[156:159], v[40:43]
	s_waitcnt lgkmcnt(0)
	v_mfma_f32_16x16x32_bf16 v[68:71], v[248:251], v[144:147], v[68:71]
	v_mfma_f32_16x16x32_bf16 v[76:79], v[248:251], v[148:151], v[76:79]
	v_mfma_f32_16x16x32_bf16 v[36:39], v[248:251], v[152:155], v[36:39]
	v_mfma_f32_16x16x32_bf16 v[44:47], v[248:251], v[156:159], v[44:47]
	global_load_dwordx4 v[144:147], v[198:199], off
	global_load_dwordx4 v[148:151], v[198:199], off offset:256
	global_load_dwordx4 v[152:155], v[200:201], off
	global_load_dwordx4 v[156:159], v[200:201], off offset:256
	s_waitcnt vmcnt(10)
	s_barrier
	s_add_i32 s1, s1, 6
	s_cmp_lt_u32 s1, 30
	s_cbranch_scc1 .Lg16_proj_k
	ds_read_b128 v[236:239], v196 offset:0
	ds_read_b128 v[240:243], v162 offset:0
	ds_read_b128 v[244:247], v196 offset:2048
	ds_read_b128 v[248:251], v162 offset:2048
	s_waitcnt vmcnt(6) lgkmcnt(3)
	v_mfma_f32_16x16x32_bf16 v[16:19], v[236:239], v[128:131], v[16:19]
	v_mfma_f32_16x16x32_bf16 v[24:27], v[236:239], v[132:135], v[24:27]
	v_mfma_f32_16x16x32_bf16 v[0:3], v[236:239], v[136:139], v[0:3]
	v_mfma_f32_16x16x32_bf16 v[8:11], v[236:239], v[140:143], v[8:11]
	ds_read_b128 v[236:239], v196 offset:4096
	s_waitcnt lgkmcnt(3)
	v_mfma_f32_16x16x32_bf16 v[20:23], v[240:243], v[128:131], v[20:23]
	v_mfma_f32_16x16x32_bf16 v[28:31], v[240:243], v[132:135], v[28:31]
	v_mfma_f32_16x16x32_bf16 v[4:7], v[240:243], v[136:139], v[4:7]
	v_mfma_f32_16x16x32_bf16 v[12:15], v[240:243], v[140:143], v[12:15]
	ds_read_b128 v[240:243], v162 offset:4096
	s_waitcnt lgkmcnt(3)
	v_mfma_f32_16x16x32_bf16 v[112:115], v[244:247], v[128:131], v[112:115]
	v_mfma_f32_16x16x32_bf16 v[120:123], v[244:247], v[132:135], v[120:123]
	v_mfma_f32_16x16x32_bf16 v[96:99], v[244:247], v[136:139], v[96:99]
	v_mfma_f32_16x16x32_bf16 v[104:107], v[244:247], v[140:143], v[104:107]
	ds_read_b128 v[244:247], v196 offset:6144
	s_waitcnt lgkmcnt(3)
	v_mfma_f32_16x16x32_bf16 v[116:119], v[248:251], v[128:131], v[116:119]
	v_mfma_f32_16x16x32_bf16 v[124:127], v[248:251], v[132:135], v[124:127]
	v_mfma_f32_16x16x32_bf16 v[100:103], v[248:251], v[136:139], v[100:103]
	v_mfma_f32_16x16x32_bf16 v[108:111], v[248:251], v[140:143], v[108:111]
	ds_read_b128 v[248:251], v162 offset:6144
	s_waitcnt lgkmcnt(3)
	v_mfma_f32_16x16x32_bf16 v[80:83], v[236:239], v[128:131], v[80:83]
	v_mfma_f32_16x16x32_bf16 v[88:91], v[236:239], v[132:135], v[88:91]
	v_mfma_f32_16x16x32_bf16 v[48:51], v[236:239], v[136:139], v[48:51]
	v_mfma_f32_16x16x32_bf16 v[56:59], v[236:239], v[140:143], v[56:59]
	s_waitcnt lgkmcnt(2)
	v_mfma_f32_16x16x32_bf16 v[84:87], v[240:243], v[128:131], v[84:87]
	v_mfma_f32_16x16x32_bf16 v[92:95], v[240:243], v[132:135], v[92:95]
	v_mfma_f32_16x16x32_bf16 v[52:55], v[240:243], v[136:139], v[52:55]
	v_mfma_f32_16x16x32_bf16 v[60:63], v[240:243], v[140:143], v[60:63]
	s_waitcnt lgkmcnt(1)
	v_mfma_f32_16x16x32_bf16 v[64:67], v[244:247], v[128:131], v[64:67]
	v_mfma_f32_16x16x32_bf16 v[72:75], v[244:247], v[132:135], v[72:75]
	v_mfma_f32_16x16x32_bf16 v[32:35], v[244:247], v[136:139], v[32:35]
	v_mfma_f32_16x16x32_bf16 v[40:43], v[244:247], v[140:143], v[40:43]
	s_waitcnt lgkmcnt(0)
	v_mfma_f32_16x16x32_bf16 v[68:71], v[248:251], v[128:131], v[68:71]
	v_mfma_f32_16x16x32_bf16 v[76:79], v[248:251], v[132:135], v[76:79]
	v_mfma_f32_16x16x32_bf16 v[36:39], v[248:251], v[136:139], v[36:39]
	v_mfma_f32_16x16x32_bf16 v[44:47], v[248:251], v[140:143], v[44:47]
	s_waitcnt vmcnt(4)
	s_barrier
	ds_read_b128 v[236:239], v196 offset:8192
	ds_read_b128 v[240:243], v162 offset:8192
	ds_read_b128 v[244:247], v196 offset:10240
	ds_read_b128 v[248:251], v162 offset:10240
	s_waitcnt vmcnt(0) lgkmcnt(3)
	v_mfma_f32_16x16x32_bf16 v[16:19], v[236:239], v[144:147], v[16:19]
	v_mfma_f32_16x16x32_bf16 v[24:27], v[236:239], v[148:151], v[24:27]
	v_mfma_f32_16x16x32_bf16 v[0:3], v[236:239], v[152:155], v[0:3]
	v_mfma_f32_16x16x32_bf16 v[8:11], v[236:239], v[156:159], v[8:11]
	ds_read_b128 v[236:239], v196 offset:12288
	s_waitcnt lgkmcnt(3)
	v_mfma_f32_16x16x32_bf16 v[20:23], v[240:243], v[144:147], v[20:23]
	v_mfma_f32_16x16x32_bf16 v[28:31], v[240:243], v[148:151], v[28:31]
	v_mfma_f32_16x16x32_bf16 v[4:7], v[240:243], v[152:155], v[4:7]
	v_mfma_f32_16x16x32_bf16 v[12:15], v[240:243], v[156:159], v[12:15]
	ds_read_b128 v[240:243], v162 offset:12288
	s_waitcnt lgkmcnt(3)
	v_mfma_f32_16x16x32_bf16 v[112:115], v[244:247], v[144:147], v[112:115]
	v_mfma_f32_16x16x32_bf16 v[120:123], v[244:247], v[148:151], v[120:123]
	v_mfma_f32_16x16x32_bf16 v[96:99], v[244:247], v[152:155], v[96:99]
	v_mfma_f32_16x16x32_bf16 v[104:107], v[244:247], v[156:159], v[104:107]
	ds_read_b128 v[244:247], v196 offset:14336
	s_waitcnt lgkmcnt(3)
	v_mfma_f32_16x16x32_bf16 v[116:119], v[248:251], v[144:147], v[116:119]
	v_mfma_f32_16x16x32_bf16 v[124:127], v[248:251], v[148:151], v[124:127]
	v_mfma_f32_16x16x32_bf16 v[100:103], v[248:251], v[152:155], v[100:103]
	v_mfma_f32_16x16x32_bf16 v[108:111], v[248:251], v[156:159], v[108:111]
	ds_read_b128 v[248:251], v162 offset:14336
	s_waitcnt lgkmcnt(3)
	v_mfma_f32_16x16x32_bf16 v[80:83], v[236:239], v[144:147], v[80:83]
	v_mfma_f32_16x16x32_bf16 v[88:91], v[236:239], v[148:151], v[88:91]
	v_mfma_f32_16x16x32_bf16 v[48:51], v[236:239], v[152:155], v[48:51]
	v_mfma_f32_16x16x32_bf16 v[56:59], v[236:239], v[156:159], v[56:59]
	s_waitcnt lgkmcnt(2)
	v_mfma_f32_16x16x32_bf16 v[84:87], v[240:243], v[144:147], v[84:87]
	v_mfma_f32_16x16x32_bf16 v[92:95], v[240:243], v[148:151], v[92:95]
	v_mfma_f32_16x16x32_bf16 v[52:55], v[240:243], v[152:155], v[52:55]
	v_mfma_f32_16x16x32_bf16 v[60:63], v[240:243], v[156:159], v[60:63]
	s_waitcnt lgkmcnt(1)
	v_mfma_f32_16x16x32_bf16 v[64:67], v[244:247], v[144:147], v[64:67]
	v_mfma_f32_16x16x32_bf16 v[72:75], v[244:247], v[148:151], v[72:75]
	v_mfma_f32_16x16x32_bf16 v[32:35], v[244:247], v[152:155], v[32:35]
	v_mfma_f32_16x16x32_bf16 v[40:43], v[244:247], v[156:159], v[40:43]
	s_waitcnt lgkmcnt(0)
	v_mfma_f32_16x16x32_bf16 v[68:71], v[248:251], v[144:147], v[68:71]
	v_mfma_f32_16x16x32_bf16 v[76:79], v[248:251], v[148:151], v[76:79]
	v_mfma_f32_16x16x32_bf16 v[36:39], v[248:251], v[152:155], v[36:39]
	v_mfma_f32_16x16x32_bf16 v[44:47], v[248:251], v[156:159], v[44:47]
	s_barrier
	s_nop 7
	s_nop 1
	s_waitcnt vmcnt(0)
	s_waitcnt vmcnt(0)
	v_and_b32_e32 v128, 63, v179
	v_lshrrev_b32_e32 v129, 6, v179
	s_lshl_b32 s20, s2, 8
	s_cmp_eq_u32 s0, 23
	s_cbranch_scc1 .Lpe_proj_ab
	v_readlane_b32 s14, v254, 15
	v_readlane_b32 s15, v254, 16
	v_readlane_b32 s16, v254, 17
	v_readlane_b32 s17, v254, 18
	s_movk_i32 s22, 0x900
	s_movk_i32 s23, 0x300
	s_cmp_lt_u32 s0, 20
	s_cselect_b32 s14, s14, s16
	s_cselect_b32 s15, s15, s17
	s_cselect_b32 s18, s22, s23
	s_movk_i32 s22, 0xf500
	s_movk_i32 s23, 0xec00
	s_cselect_b32 s19, s22, s23
	s_movk_i32 s22, 0xb00
	s_cmp_lt_u32 s0, 11
	s_cselect_b32 s14, s66, s14
	s_cselect_b32 s15, s67, s15
	s_cselect_b32 s18, s22, s18
	s_cselect_b32 s19, 0, s19
	s_mul_hi_u32 s21, s20, s18
	s_mul_i32 s20, s20, s18
	s_lshl_b32 s22, s0, 8
	s_add_i32 s22, s22, s19
	s_add_u32 s12, s14, s20
	s_addc_u32 s13, s15, s21
	s_add_u32 s12, s12, s22
	s_addc_u32 s13, s13, 0
	v_mul_u32_u24_e32 v188, 0x2400, v129
	v_and_b32_e32 v189, 15, v128
	v_mul_u32_u24_e32 v189, 0x90, v189
	v_add_u32_e32 v130, v188, v189
	v_lshrrev_b32_e32 v189, 4, v128
	v_lshl_add_u32 v130, v189, 4, v130
	v_lshrrev_b32_e32 v189, 3, v128
	v_mul_u32_u24_e32 v132, 0x90, v189
	v_add_u32_e32 v131, v188, v132
	v_and_b32_e32 v188, 7, v128
	v_lshlrev_b32_e32 v188, 4, v188
	v_add_u32_e32 v131, v131, v188
	v_lshl_add_u32 v189, v129, 6, v189
	v_add_u32_e32 v132, 0, v189
	v_add_u32_e32 v133, 8, v189
	v_add_u32_e32 v134, 16, v189
	v_add_u32_e32 v135, 24, v189
	v_add_u32_e32 v136, 32, v189
	v_add_u32_e32 v137, 40, v189
	v_add_u32_e32 v138, 48, v189
	v_add_u32_e32 v139, 56, v189
	v_mul_lo_u32 v132, v132, s18
	v_mul_lo_u32 v133, v133, s18
	v_mul_lo_u32 v134, v134, s18
	v_mul_lo_u32 v135, v135, s18
	v_mul_lo_u32 v136, v136, s18
	v_mul_lo_u32 v137, v137, s18
	v_mul_lo_u32 v138, v138, s18
	v_mul_lo_u32 v139, v139, s18
	v_add_u32_e32 v132, v132, v188
	v_add_u32_e32 v133, v133, v188
	v_add_u32_e32 v134, v134, v188
	v_add_u32_e32 v135, v135, v188
	v_add_u32_e32 v136, v136, v188
	v_add_u32_e32 v137, v137, v188
	v_add_u32_e32 v138, v138, v188
	v_add_u32_e32 v139, v139, v188
	v_cvt_pk_bf16_f32 v140, v16, v17
	v_cvt_pk_bf16_f32 v141, v18, v19
	v_cvt_pk_bf16_f32 v142, v20, v21
	v_cvt_pk_bf16_f32 v143, v22, v23
	ds_write_b128 v130, v[140:143]
	v_cvt_pk_bf16_f32 v144, v112, v113
	v_cvt_pk_bf16_f32 v145, v114, v115
	v_cvt_pk_bf16_f32 v146, v116, v117
	v_cvt_pk_bf16_f32 v147, v118, v119
	ds_write_b128 v130, v[144:147] offset:64
	v_cvt_pk_bf16_f32 v140, v24, v25
	v_cvt_pk_bf16_f32 v141, v26, v27
	v_cvt_pk_bf16_f32 v142, v28, v29
	v_cvt_pk_bf16_f32 v143, v30, v31
	ds_write_b128 v130, v[140:143] offset:2304
	v_cvt_pk_bf16_f32 v144, v120, v121
	v_cvt_pk_bf16_f32 v145, v122, v123
	v_cvt_pk_bf16_f32 v146, v124, v125
	v_cvt_pk_bf16_f32 v147, v126, v127
	ds_write_b128 v130, v[144:147] offset:2368
	v_cvt_pk_bf16_f32 v140, v0, v1
	v_cvt_pk_bf16_f32 v141, v2, v3
	v_cvt_pk_bf16_f32 v142, v4, v5
	v_cvt_pk_bf16_f32 v143, v6, v7
	ds_write_b128 v130, v[140:143] offset:4608
	v_cvt_pk_bf16_f32 v144, v96, v97
	v_cvt_pk_bf16_f32 v145, v98, v99
	v_cvt_pk_bf16_f32 v146, v100, v101
	v_cvt_pk_bf16_f32 v147, v102, v103
	ds_write_b128 v130, v[144:147] offset:4672
	v_cvt_pk_bf16_f32 v140, v8, v9
	v_cvt_pk_bf16_f32 v141, v10, v11
	v_cvt_pk_bf16_f32 v142, v12, v13
	v_cvt_pk_bf16_f32 v143, v14, v15
	ds_write_b128 v130, v[140:143] offset:6912
	v_cvt_pk_bf16_f32 v144, v104, v105
	v_cvt_pk_bf16_f32 v145, v106, v107
	v_cvt_pk_bf16_f32 v146, v108, v109
	v_cvt_pk_bf16_f32 v147, v110, v111
	ds_write_b128 v130, v[144:147] offset:6976
	s_waitcnt lgkmcnt(0)
	ds_read_b128 v[148:151], v131
	ds_read_b128 v[152:155], v131 offset:1152
	ds_read_b128 v[156:159], v131 offset:2304
	ds_read_b128 v[160:163], v131 offset:3456
	ds_read_b128 v[164:167], v131 offset:4608
	ds_read_b128 v[168:171], v131 offset:5760
	ds_read_b128 v[172:175], v131 offset:6912
	ds_read_b128 v[184:187], v131 offset:8064
	s_waitcnt lgkmcnt(7)
	global_store_dwordx4 v132, v[148:151], s[12:13]
	s_waitcnt lgkmcnt(6)
	global_store_dwordx4 v133, v[152:155], s[12:13]
	s_waitcnt lgkmcnt(5)
	global_store_dwordx4 v134, v[156:159], s[12:13]
	s_waitcnt lgkmcnt(4)
	global_store_dwordx4 v135, v[160:163], s[12:13]
	s_waitcnt lgkmcnt(3)
	global_store_dwordx4 v136, v[164:167], s[12:13]
	s_waitcnt lgkmcnt(2)
	global_store_dwordx4 v137, v[168:171], s[12:13]
	s_waitcnt lgkmcnt(1)
	global_store_dwordx4 v138, v[172:175], s[12:13]
	s_waitcnt lgkmcnt(0)
	global_store_dwordx4 v139, v[184:187], s[12:13]
	v_cvt_pk_bf16_f32 v140, v80, v81
	v_cvt_pk_bf16_f32 v141, v82, v83
	v_cvt_pk_bf16_f32 v142, v84, v85
	v_cvt_pk_bf16_f32 v143, v86, v87
	ds_write_b128 v130, v[140:143]
	v_cvt_pk_bf16_f32 v144, v64, v65
	v_cvt_pk_bf16_f32 v145, v66, v67
	v_cvt_pk_bf16_f32 v146, v68, v69
	v_cvt_pk_bf16_f32 v147, v70, v71
	ds_write_b128 v130, v[144:147] offset:64
	v_cvt_pk_bf16_f32 v140, v88, v89
	v_cvt_pk_bf16_f32 v141, v90, v91
	v_cvt_pk_bf16_f32 v142, v92, v93
	v_cvt_pk_bf16_f32 v143, v94, v95
	ds_write_b128 v130, v[140:143] offset:2304
	v_cvt_pk_bf16_f32 v144, v72, v73
	v_cvt_pk_bf16_f32 v145, v74, v75
	v_cvt_pk_bf16_f32 v146, v76, v77
	v_cvt_pk_bf16_f32 v147, v78, v79
	ds_write_b128 v130, v[144:147] offset:2368
	v_cvt_pk_bf16_f32 v140, v48, v49
	v_cvt_pk_bf16_f32 v141, v50, v51
	v_cvt_pk_bf16_f32 v142, v52, v53
	v_cvt_pk_bf16_f32 v143, v54, v55
	ds_write_b128 v130, v[140:143] offset:4608
	v_cvt_pk_bf16_f32 v144, v32, v33
	v_cvt_pk_bf16_f32 v145, v34, v35
	v_cvt_pk_bf16_f32 v146, v36, v37
	v_cvt_pk_bf16_f32 v147, v38, v39
	ds_write_b128 v130, v[144:147] offset:4672
	v_cvt_pk_bf16_f32 v140, v56, v57
	v_cvt_pk_bf16_f32 v141, v58, v59
	v_cvt_pk_bf16_f32 v142, v60, v61
	v_cvt_pk_bf16_f32 v143, v62, v63
	ds_write_b128 v130, v[140:143] offset:6912
	v_cvt_pk_bf16_f32 v144, v40, v41
	v_cvt_pk_bf16_f32 v145, v42, v43
	v_cvt_pk_bf16_f32 v146, v44, v45
	v_cvt_pk_bf16_f32 v147, v46, v47
	ds_write_b128 v130, v[144:147] offset:6976
	s_waitcnt lgkmcnt(0)
	ds_read_b128 v[148:151], v131
	ds_read_b128 v[152:155], v131 offset:1152
	ds_read_b128 v[156:159], v131 offset:2304
	ds_read_b128 v[160:163], v131 offset:3456
	ds_read_b128 v[164:167], v131 offset:4608
	ds_read_b128 v[168:171], v131 offset:5760
	ds_read_b128 v[172:175], v131 offset:6912
	ds_read_b128 v[184:187], v131 offset:8064
	s_waitcnt lgkmcnt(7)
	global_store_dwordx4 v132, v[148:151], s[12:13] offset:128
	s_waitcnt lgkmcnt(6)
	global_store_dwordx4 v133, v[152:155], s[12:13] offset:128
	s_waitcnt lgkmcnt(5)
	global_store_dwordx4 v134, v[156:159], s[12:13] offset:128
	s_waitcnt lgkmcnt(4)
	global_store_dwordx4 v135, v[160:163], s[12:13] offset:128
	s_waitcnt lgkmcnt(3)
	global_store_dwordx4 v136, v[164:167], s[12:13] offset:128
	s_waitcnt lgkmcnt(2)
	global_store_dwordx4 v137, v[168:171], s[12:13] offset:128
	s_waitcnt lgkmcnt(1)
	global_store_dwordx4 v138, v[172:175], s[12:13] offset:128
	s_waitcnt lgkmcnt(0)
	global_store_dwordx4 v139, v[184:187], s[12:13] offset:128
	s_branch .Lpe_proj_end
.Lpe_proj_ab:
	v_readlane_b32 s14, v254, 19
	v_readlane_b32 s15, v254, 20
	s_mul_i32 s20, s20, 0x60
	s_add_u32 s12, s14, s20
	s_addc_u32 s13, s15, 0
	v_and_b32_e32 v189, 15, v128
	v_lshl_add_u32 v189, v129, 6, v189
	v_mul_u32_u24_e32 v189, 0x60, v189
	v_lshrrev_b32_e32 v188, 4, v128
	v_lshl_add_u32 v189, v188, 5, v189
	v_cmp_gt_u32_e32 vcc, 48, v128
	s_and_saveexec_b64 s[14:15], vcc
	global_store_dwordx4 v189, v[16:19], s[12:13]
	global_store_dwordx4 v189, v[20:23], s[12:13] offset:16
	global_store_dwordx4 v189, v[24:27], s[12:13] offset:1536
	global_store_dwordx4 v189, v[28:31], s[12:13] offset:1552
	s_add_u32 s12, s12, 0xc00
	s_addc_u32 s13, s13, 0
	global_store_dwordx4 v189, v[0:3], s[12:13]
	global_store_dwordx4 v189, v[4:7], s[12:13] offset:16
	global_store_dwordx4 v189, v[8:11], s[12:13] offset:1536
	global_store_dwordx4 v189, v[12:15], s[12:13] offset:1552
	s_mov_b64 exec, s[14:15]
